# EA: epilogue alignment - on a GEMM call's last unit the first wave half takes one extra barrier at epilogue entry and the second half one at epilogue exit, so both halves run the epilogue together ins
# speedup vs baseline: 1.0171x; 1.0171x over previous
; #define LAS __attribute__((address_space(3)))
; #define PG8_WAIT_V(n) asm volatile("s_waitcnt vmcnt(" #n ")" ::: "memory")
; #define PG8_BAR __builtin_amdgcn_s_barrier()
; __device__ __forceinline__ bool gemm_phase(LAS unsigned char* lds, int l, int sub, int gi, bool dry = false) {
;     ...
;         __builtin_amdgcn_sched_barrier(0); asm volatile("" ::: "memory");
;         if (!dry) { GD g2; make_gd((LAS const Params*)(lds + PRM_OFF), l, sub, gi, g2); gemm_epilogue(lds, g2, acc, cur); }
;         if (!has_next) break;
; #pragma unroll
;         for (int a = 0; a < 2; ++a)
; #pragma unroll
;             for (int b = 0; b < 2; ++b)
; #pragma unroll
;                 for (int m = 0; m < 4; ++m)
; #pragma unroll
;                     for (int n = 0; n < 2; ++n) acc[a][b][m][n] = (f32x4){0.f, 0.f, 0.f, 0.f};
;         cur = nxt; cA = nA; cB = nB; ++ui;
;     }
;     PG8_WAIT_V(0);
;     if (wr == 0) PG8_BAR;
;     PG8_BAR;
.LBB0_309:
	s_cmp_eq_u64 s[52:53], 0
	s_cbranch_scc1 .Lmy_ea_e
	v_readfirstlane_b32 s2, v210
	s_nop 3
	s_lshr_b32 s2, s2, 8
	s_cmp_lg_u32 s2, 1
	s_cbranch_scc1 .Lmy_ea_e
	s_barrier

; #define LAS __attribute__((address_space(3)))
; __device__ __forceinline__ bool gemm_phase(LAS unsigned char* lds, int l, int sub, int gi, bool dry = false) {
;     ...
;         __builtin_amdgcn_sched_barrier(0); asm volatile("" ::: "memory");
;         if (!dry) { GD g2; make_gd((LAS const Params*)(lds + PRM_OFF), l, sub, gi, g2); gemm_epilogue(lds, g2, acc, cur); }
.LBB0_385:
	s_cmp_eq_u64 s[52:53], 0
	s_cbranch_scc1 .Lmy_ea_s
	v_readfirstlane_b32 s88, v210
	s_nop 3
	s_lshr_b32 s88, s88, 8
	s_cmp_lg_u32 s88, 0
	s_cbranch_scc1 .Lmy_ea_s
	s_barrier

; #define GAS __attribute__((address_space(1)))
; __device__ __forceinline__ void gemm_epilogue(LAS unsigned char* lds, const GD& gd, const f32x4 (&acc)[2][2][4][2], const Unit& u) {
;     ...
; #pragma unroll
;         for (int am = 0; am < 8 / MBR; ++am) {
;             const int ai = (am * MBR) >> 2, m0 = (am * MBR) & 3;
;             f32x4 xi[MBR][2][2];
; #pragma unroll
;             for (int mm = 0; mm < MBR; ++mm)
; #pragma unroll
;                 for (int bj = 0; bj < 2; ++bj)
; #pragma unroll
;                     for (int n = 0; n < 2; ++n) xi[mm][bj][n] = *(GAS const f32x4*)(xin + xoff + (ai * HALF + (m0 + mm) * 16) * DM + bj * HALF + n * 16);
;             asm volatile("" ::: "memory");
; #pragma unroll
;             for (int mm = 0; mm < MBR; ++mm)
; #pragma unroll
;                 for (int bj = 0; bj < 2; ++bj)
; #pragma unroll
;                     for (int n = 0; n < 2; ++n) *(GAS f32x4*)(xout + xoff + (ai * HALF + (m0 + mm) * 16) * DM + bj * HALF + n * 16) = xi[mm][bj][n] + gv[bj][n] * acc[ai][bj][m0 + mm][n];
;         }
;         return;
.Lmy_fn_done:
	s_nop 3
	s_branch .LBB0_622
